# code placement: one 4-byte s_nop at kernel entry (whole instruction stream shifted by 4 bytes, flips its mod-8 phase)
# baseline (speedup 1.0000x reference)
_Z10fwd_kernel4Args:
	s_nop 0
	s_mov_b64 s[96:97], s[0:1]
	s_load_dwordx2 s[92:93], s[0:1], 0xb0
	s_nop 0
	s_load_dword s0, s[0:1], 0xb8
	s_add_u32 s4, s96, 0xb0
	v_and_b32_e32 v1, 0x3ff, v0
	s_mov_b32 s90, s2
	s_addc_u32 s5, s97, 0
	s_waitcnt lgkmcnt(0)
	v_writelane_b32 v254, s0, 0
	v_cmp_gt_u32_e32 vcc, 2, v1
	s_and_saveexec_b64 s[0:1], vcc
	v_lshl_add_u32 v2, v1, 2, 0
	v_add_u32_e32 v2, 0x20100, v2
	v_mov_b32_e32 v3, 0
	ds_write_b32 v2, v3
	s_or_b64 exec, exec, s[0:1]
	s_waitcnt lgkmcnt(0)
	s_barrier
	s_load_dwordx2 s[94:95], s[96:97], 0xa0
	s_getreg_b32 s6, hwreg(HW_REG_XCC_ID, 0, 4)
	v_cmp_eq_u32_e64 s[74:75], 0, v1
	s_waitcnt lgkmcnt(0)
	s_add_u32 s0, s94, 0x4c0000
	s_addc_u32 s1, s95, 0
	v_writelane_b32 v254, s0, 1
	s_nop 1
	v_writelane_b32 v254, s1, 2
	s_and_saveexec_b64 s[0:1], s[74:75]
	s_cbranch_execz .LBB0_5
	s_mov_b64 s[2:3], exec
	v_mbcnt_lo_u32_b32 v2, s2, 0
	v_mbcnt_hi_u32_b32 v2, s3, v2
	v_cmp_eq_u32_e32 vcc, 0, v2
	s_and_b64 s[8:9], exec, vcc
	s_mov_b64 exec, s[8:9]
	s_cbranch_execz .LBB0_5
	s_lshl_b32 s6, s6, 8
	s_bcnt1_i32_b64 s2, s[2:3]
	s_and_b32 s6, s6, 0xf00
	v_mov_b32_e32 v3, s2
	v_readlane_b32 s2, v254, 1
	v_mov_b32_e32 v2, s6
	v_readlane_b32 s3, v254, 2
	s_nop 4
	global_atomic_add v2, v3, s[2:3] offset:1024
